# v83 + phase 4b: x rows / post_g of pass 2's first half requested right after the GEMM, before pass 1 and the M-tile meeting
# speedup vs baseline: 1.0237x; 1.0027x over previous
.LBB0_589:
	s_or_b64 exec, exec, s[2:3]
	v_add_u32_e32 v142, 0x8000, v219
	v_add_u32_e32 v145, 0xc000, v219
	s_waitcnt vmcnt(0)
	s_barrier
	s_load_dwordx2 s[12:13], s[0:1], 0x0
	s_load_dwordx2 s[14:15], s[0:1], 0x80
	v_ashrrev_i32_e32 v244, 2, v140
	v_and_b32_e32 v244, 0xffffffe0, v244
	v_bfe_u32 v245, v140, 4, 2
	s_add_i32 s16, s65, s64
	v_add3_u32 v244, s16, v245, v244
	v_ashrrev_i32_e32 v246, 6, v140
	v_lshlrev_b32_e32 v246, 7, v246
	v_and_b32_e32 v246, 0x80, v246
	v_and_b32_e32 v247, 63, v140
	v_lshlrev_b32_e32 v247, 3, v247
	v_and_b32_e32 v247, 0x78, v247
	v_or3_b32 v246, v246, s62, v247
	v_lshlrev_b32_e32 v246, 2, v246
	v_mov_b32_e32 v247, 0
	s_waitcnt lgkmcnt(0)
	v_lshl_add_u64 v[248:249], s[14:15], 0, v[246:247]
	global_load_dwordx4 v[220:223], v[248:249], off
	global_load_dwordx4 v[224:227], v[248:249], off offset:16
	v_lshl_add_u64 v[246:247], s[12:13], 0, v[246:247]
	v_add_u32_e32 v248, 0, v244
	v_ashrrev_i32_e32 v249, 31, v248
	v_lshlrev_b64 v[248:249], 12, v[248:249]
	v_lshl_add_u64 v[248:249], v[246:247], 0, v[248:249]
	global_load_dwordx4 v[150:153], v[248:249], off
	global_load_dwordx4 v[154:157], v[248:249], off offset:16
	v_add_u32_e32 v248, 4, v244
	v_ashrrev_i32_e32 v249, 31, v248
	v_lshlrev_b64 v[248:249], 12, v[248:249]
	v_lshl_add_u64 v[248:249], v[246:247], 0, v[248:249]
	global_load_dwordx4 v[158:161], v[248:249], off
	global_load_dwordx4 v[162:165], v[248:249], off offset:16
	v_add_u32_e32 v248, 8, v244
	v_ashrrev_i32_e32 v249, 31, v248
	v_lshlrev_b64 v[248:249], 12, v[248:249]
	v_lshl_add_u64 v[248:249], v[246:247], 0, v[248:249]
	global_load_dwordx4 v[166:169], v[248:249], off
	global_load_dwordx4 v[170:173], v[248:249], off offset:16
	v_add_u32_e32 v248, 12, v244
	v_ashrrev_i32_e32 v249, 31, v248
	v_lshlrev_b64 v[248:249], 12, v[248:249]
	v_lshl_add_u64 v[248:249], v[246:247], 0, v[248:249]
	global_load_dwordx4 v[174:177], v[248:249], off
	global_load_dwordx4 v[178:181], v[248:249], off offset:16
	v_add_u32_e32 v248, 16, v244
	v_ashrrev_i32_e32 v249, 31, v248
	v_lshlrev_b64 v[248:249], 12, v[248:249]
	v_lshl_add_u64 v[248:249], v[246:247], 0, v[248:249]
	global_load_dwordx4 v[182:185], v[248:249], off
	global_load_dwordx4 v[186:189], v[248:249], off offset:16
	v_add_u32_e32 v248, 20, v244
	v_ashrrev_i32_e32 v249, 31, v248
	v_lshlrev_b64 v[248:249], 12, v[248:249]
	v_lshl_add_u64 v[248:249], v[246:247], 0, v[248:249]
	global_load_dwordx4 v[190:193], v[248:249], off
	global_load_dwordx4 v[194:197], v[248:249], off offset:16
	v_add_u32_e32 v248, 24, v244
	v_ashrrev_i32_e32 v249, 31, v248
	v_lshlrev_b64 v[248:249], 12, v[248:249]
	v_lshl_add_u64 v[248:249], v[246:247], 0, v[248:249]
	global_load_dwordx4 v[198:201], v[248:249], off
	global_load_dwordx4 v[202:205], v[248:249], off offset:16
	v_add_u32_e32 v248, 28, v244
	v_ashrrev_i32_e32 v249, 31, v248
	v_lshlrev_b64 v[248:249], 12, v[248:249]
	v_lshl_add_u64 v[248:249], v[246:247], 0, v[248:249]
	global_load_dwordx4 v[206:209], v[248:249], off
	global_load_dwordx4 v[210:213], v[248:249], off offset:16
	v_add_u32_e32 v130, 0x400, v219
	v_add_u32_e32 v133, 0x800, v219
	v_add_u32_e32 v136, 0xc00, v219
	v_add_u32_e32 v137, 0x4000, v219
	v_add_u32_e32 v138, 0x4400, v219
	v_add_u32_e32 v139, 0x4800, v219
	v_add_u32_e32 v141, 0x4c00, v219
	ds_write2_b32 v142, v72, v76 offset0:128 offset1:144
	v_add_u32_e32 v142, 0x8400, v219
	v_add_u32_e32 v143, 0x8800, v219
	v_add_u32_e32 v144, 0x8c00, v219
	ds_write2_b32 v145, v64, v68 offset0:192 offset1:208
	v_add_u32_e32 v145, 0xc400, v219
	v_add_u32_e32 v146, 0xc800, v219
	v_add_u32_e32 v147, 0xcc00, v219
	s_add_u32 s2, s38, 0xe9c8800
	v_ashrrev_i32_e32 v135, 2, v140
	ds_write2_b32 v219, v108, v124 offset1:16
	ds_write2_b32 v130, v109, v125 offset0:4 offset1:20
	ds_write2_b32 v133, v110, v126 offset0:8 offset1:24
	ds_write2_b32 v136, v111, v127 offset0:12 offset1:28
	ds_write2_b32 v137, v80, v88 offset0:64 offset1:80
	ds_write2_b32 v138, v81, v89 offset0:68 offset1:84
	ds_write2_b32 v139, v82, v90 offset0:72 offset1:88
	ds_write2_b32 v141, v83, v91 offset0:76 offset1:92
	ds_write2_b32 v142, v73, v77 offset0:132 offset1:148
	ds_write2_b32 v143, v74, v78 offset0:136 offset1:152
	ds_write2_b32 v144, v75, v79 offset0:140 offset1:156
	ds_write2_b32 v145, v65, v69 offset0:196 offset1:212
	ds_write2_b32 v146, v66, v70 offset0:200 offset1:216
	ds_write2_b32 v147, v67, v71 offset0:204 offset1:220
	ds_write2_b32 v219, v96, v116 offset0:128 offset1:144
	ds_write2_b32 v130, v97, v117 offset0:132 offset1:148
	ds_write2_b32 v133, v98, v118 offset0:136 offset1:152
	ds_write2_b32 v136, v99, v119 offset0:140 offset1:156
	ds_write2_b32 v137, v100, v120 offset0:192 offset1:208
	ds_write2_b32 v138, v101, v121 offset0:196 offset1:212
	ds_write2_b32 v139, v102, v122 offset0:200 offset1:216
	ds_write2_b32 v141, v103, v123 offset0:204 offset1:220
	ds_write2_b32 v142, v92, v112 offset1:16
	ds_write2_b32 v143, v93, v113 offset0:4 offset1:20
	ds_write2_b32 v144, v94, v114 offset0:8 offset1:24
	v_add_u32_e32 v130, 0x9000, v219
	s_addc_u32 s3, s39, 0
	v_and_b32_e32 v128, 0xffffffe0, v135
	v_bfe_u32 v129, v140, 4, 2
	ds_write2_b32 v130, v95, v115 offset0:12 offset1:28
	ds_write2_b32 v145, v84, v104 offset0:64 offset1:80
	ds_write2_b32 v146, v85, v105 offset0:68 offset1:84
	ds_write2_b32 v147, v86, v106 offset0:72 offset1:88
	v_add_u32_e32 v130, 0xd000, v219
	s_add_i32 s65, s65, s64
	ds_write2_b32 v130, v87, v107 offset0:76 offset1:92
	v_add3_u32 v130, s65, v129, v128
	v_lshrrev_b32_e32 v128, 5, v135
	s_mov_b32 s6, 0x8200
	v_lshlrev_b32_e32 v133, 3, v140
	v_and_b32_e32 v134, 15, v140
	v_mul_lo_u32 v128, v128, s6
	v_mul_u32_u24_e32 v129, 0x410, v129
	v_and_b32_e32 v133, 0x200, v133
	v_lshlrev_b32_e32 v132, 5, v134
	v_add3_u32 v128, v128, v129, v133
	v_and_b32_e32 v131, 63, v140
	v_cmp_eq_u32_e32 vcc, 0, v134
	v_add3_u32 v136, v128, v132, 0
	v_mov_b32_e32 v128, v130
	s_waitcnt lgkmcnt(0)
	s_barrier
	s_branch .LBB0_591

.LBB0_606:
	s_or_b64 exec, exec, s[6:7]
	s_barrier
	s_barrier
	ds_write2_b32 v219, v108, v124 offset1:16
	v_add_u32_e32 v108, 0x400, v219
	ds_write2_b32 v108, v109, v125 offset0:4 offset1:20
	v_add_u32_e32 v109, 0x800, v219
	ds_write2_b32 v109, v110, v126 offset0:8 offset1:24
	v_add_u32_e32 v110, 0xc00, v219
	ds_write2_b32 v110, v111, v127 offset0:12 offset1:28
	v_add_u32_e32 v111, 0x4000, v219
	ds_write2_b32 v111, v80, v88 offset0:64 offset1:80
	v_add_u32_e32 v80, 0x4400, v219
	ds_write2_b32 v80, v81, v89 offset0:68 offset1:84
	v_add_u32_e32 v81, 0x4800, v219
	ds_write2_b32 v81, v82, v90 offset0:72 offset1:88
	v_add_u32_e32 v82, 0x4c00, v219
	ds_write2_b32 v82, v83, v91 offset0:76 offset1:92
	v_add_u32_e32 v83, 0x8000, v219
	ds_write2_b32 v83, v72, v76 offset0:128 offset1:144
	v_add_u32_e32 v72, 0x8400, v219
	ds_write2_b32 v72, v73, v77 offset0:132 offset1:148
	v_add_u32_e32 v73, 0x8800, v219
	ds_write2_b32 v73, v74, v78 offset0:136 offset1:152
	v_add_u32_e32 v74, 0x8c00, v219
	ds_write2_b32 v74, v75, v79 offset0:140 offset1:156
	v_add_u32_e32 v75, 0xc000, v219
	ds_write2_b32 v75, v64, v68 offset0:192 offset1:208
	v_add_u32_e32 v64, 0xc400, v219
	ds_write2_b32 v64, v65, v69 offset0:196 offset1:212
	v_add_u32_e32 v65, 0xc800, v219
	ds_write2_b32 v65, v66, v70 offset0:200 offset1:216
	v_add_u32_e32 v66, 0xcc00, v219
	ds_write2_b32 v66, v67, v71 offset0:204 offset1:220
	ds_write2_b32 v219, v96, v116 offset0:128 offset1:144
	ds_write2_b32 v108, v97, v117 offset0:132 offset1:148
	ds_write2_b32 v109, v98, v118 offset0:136 offset1:152
	ds_write2_b32 v110, v99, v119 offset0:140 offset1:156
	ds_write2_b32 v111, v100, v120 offset0:192 offset1:208
	ds_write2_b32 v80, v101, v121 offset0:196 offset1:212
	ds_write2_b32 v81, v102, v122 offset0:200 offset1:216
	ds_write2_b32 v82, v103, v123 offset0:204 offset1:220
	ds_write2_b32 v72, v92, v112 offset1:16
	ds_write2_b32 v73, v93, v113 offset0:4 offset1:20
	ds_write2_b32 v74, v94, v114 offset0:8 offset1:24
	v_add_u32_e32 v67, 0x9000, v219
	ds_write2_b32 v67, v95, v115 offset0:12 offset1:28
	ds_write2_b32 v64, v84, v104 offset0:64 offset1:80
	ds_write2_b32 v65, v85, v105 offset0:68 offset1:84
	ds_write2_b32 v66, v86, v106 offset0:72 offset1:88
	v_add_u32_e32 v64, 0xd000, v219
	v_ashrrev_i32_e32 v129, 6, v140
	ds_write2_b32 v64, v87, v107 offset0:76 offset1:92
	s_waitcnt lgkmcnt(0)
	s_barrier
	s_load_dwordx4 s[8:11], s[0:1], 0x80
	s_load_dwordx2 s[6:7], s[0:1], 0x0
	v_lshlrev_b32_e32 v132, 7, v129
	v_lshlrev_b32_e32 v131, 3, v131
	v_and_b32_e32 v129, 0x80, v132
	v_and_b32_e32 v131, 0x78, v131
	v_or3_b32 v129, v129, s62, v131
	v_lshlrev_b32_e32 v68, 2, v129
	v_mov_b32_e32 v69, 0
	s_waitcnt lgkmcnt(0)
	v_lshl_add_u64 v[64:65], s[8:9], 0, v[68:69]
	v_lshl_add_u64 v[66:67], s[6:7], 0, v[68:69]
	v_lshl_add_u64 v[68:69], s[10:11], 0, v[68:69]
	s_mov_b32 s6, 0
	v_mov_b32_e32 v70, 0x358637bd
	s_mov_b32 s7, 0x800000
	v_add_u32_e32 v94, 0, v130
	v_ashrrev_i32_e32 v95, 31, v94
	v_lshl_add_u64 v[92:93], v[94:95], 2, s[2:3]
	global_load_dword v228, v[92:93], off sc1
	v_add_u32_e32 v94, 4, v130
	v_ashrrev_i32_e32 v95, 31, v94
	v_lshl_add_u64 v[92:93], v[94:95], 2, s[2:3]
	global_load_dword v229, v[92:93], off sc1
	v_add_u32_e32 v94, 8, v130
	v_ashrrev_i32_e32 v95, 31, v94
	v_lshl_add_u64 v[92:93], v[94:95], 2, s[2:3]
	global_load_dword v230, v[92:93], off sc1
	v_add_u32_e32 v94, 12, v130
	v_ashrrev_i32_e32 v95, 31, v94
	v_lshl_add_u64 v[92:93], v[94:95], 2, s[2:3]
	global_load_dword v231, v[92:93], off sc1
	v_add_u32_e32 v94, 16, v130
	v_ashrrev_i32_e32 v95, 31, v94
	v_lshl_add_u64 v[92:93], v[94:95], 2, s[2:3]
	global_load_dword v232, v[92:93], off sc1
	v_add_u32_e32 v94, 20, v130
	v_ashrrev_i32_e32 v95, 31, v94
	v_lshl_add_u64 v[92:93], v[94:95], 2, s[2:3]
	global_load_dword v233, v[92:93], off sc1
	v_add_u32_e32 v94, 24, v130
	v_ashrrev_i32_e32 v95, 31, v94
	v_lshl_add_u64 v[92:93], v[94:95], 2, s[2:3]
	global_load_dword v234, v[92:93], off sc1
	v_add_u32_e32 v94, 28, v130
	v_ashrrev_i32_e32 v95, 31, v94
	v_lshl_add_u64 v[92:93], v[94:95], 2, s[2:3]
	global_load_dword v235, v[92:93], off sc1
	ds_read_b128 v[80:83], v136 offset:0
	ds_read_b128 v[84:87], v136 offset:16
	v_add_u32_e32 v90, 0, v130
	v_ashrrev_i32_e32 v91, 31, v90
	v_lshlrev_b64 v[90:91], 12, v[90:91]
	v_lshl_add_u64 v[90:91], v[68:69], 0, v[90:91]
	s_waitcnt vmcnt(7)
	v_fmamk_f32 v88, v228, 0x3a800000, v70
	v_mul_f32_e32 v89, 0x4b800000, v88
	v_cmp_gt_f32_e32 vcc, s7, v88
	s_nop 1
	v_cndmask_b32_e32 v88, v88, v89, vcc
	v_rsq_f32_e32 v88, v88
	s_nop 0
	v_mul_f32_e32 v89, 0x45800000, v88
	v_cndmask_b32_e32 v88, v88, v89, vcc
	s_waitcnt lgkmcnt(0)
	v_pk_mul_f32 v[80:81], v[80:81], v[88:89] op_sel_hi:[1,0]
	v_pk_mul_f32 v[82:83], v[82:83], v[88:89] op_sel_hi:[1,0]
	v_pk_mul_f32 v[84:85], v[84:85], v[88:89] op_sel_hi:[1,0]
	v_pk_mul_f32 v[86:87], v[86:87], v[88:89] op_sel_hi:[1,0]
	v_pk_fma_f32 v[80:81], v[220:221], v[80:81], v[150:151]
	v_pk_fma_f32 v[82:83], v[222:223], v[82:83], v[152:153]
	v_pk_fma_f32 v[84:85], v[224:225], v[84:85], v[154:155]
	v_pk_fma_f32 v[86:87], v[226:227], v[86:87], v[156:157]
	global_store_dwordx4 v[90:91], v[80:83], off
	global_store_dwordx4 v[90:91], v[84:87], off offset:16
	ds_read_b128 v[96:99], v136 offset:4160
	ds_read_b128 v[100:103], v136 offset:4176
	v_add_u32_e32 v106, 4, v130
	v_ashrrev_i32_e32 v107, 31, v106
	v_lshlrev_b64 v[106:107], 12, v[106:107]
	v_lshl_add_u64 v[106:107], v[68:69], 0, v[106:107]
	s_waitcnt vmcnt(8)
	v_fmamk_f32 v104, v229, 0x3a800000, v70
	v_mul_f32_e32 v105, 0x4b800000, v104
	v_cmp_gt_f32_e32 vcc, s7, v104
	s_nop 1
	v_cndmask_b32_e32 v104, v104, v105, vcc
	v_rsq_f32_e32 v104, v104
	s_nop 0
	v_mul_f32_e32 v105, 0x45800000, v104
	v_cndmask_b32_e32 v104, v104, v105, vcc
	s_waitcnt lgkmcnt(0)
	v_pk_mul_f32 v[96:97], v[96:97], v[104:105] op_sel_hi:[1,0]
	v_pk_mul_f32 v[98:99], v[98:99], v[104:105] op_sel_hi:[1,0]
	v_pk_mul_f32 v[100:101], v[100:101], v[104:105] op_sel_hi:[1,0]
	v_pk_mul_f32 v[102:103], v[102:103], v[104:105] op_sel_hi:[1,0]
	v_pk_fma_f32 v[96:97], v[220:221], v[96:97], v[158:159]
	v_pk_fma_f32 v[98:99], v[222:223], v[98:99], v[160:161]
	v_pk_fma_f32 v[100:101], v[224:225], v[100:101], v[162:163]
	v_pk_fma_f32 v[102:103], v[226:227], v[102:103], v[164:165]
	global_store_dwordx4 v[106:107], v[96:99], off
	global_store_dwordx4 v[106:107], v[100:103], off offset:16
	ds_read_b128 v[80:83], v136 offset:8320
	ds_read_b128 v[84:87], v136 offset:8336
	v_add_u32_e32 v90, 8, v130
	v_ashrrev_i32_e32 v91, 31, v90
	v_lshlrev_b64 v[90:91], 12, v[90:91]
	v_lshl_add_u64 v[90:91], v[68:69], 0, v[90:91]
	s_waitcnt vmcnt(9)
	v_fmamk_f32 v88, v230, 0x3a800000, v70
	v_mul_f32_e32 v89, 0x4b800000, v88
	v_cmp_gt_f32_e32 vcc, s7, v88
	s_nop 1
	v_cndmask_b32_e32 v88, v88, v89, vcc
	v_rsq_f32_e32 v88, v88
	s_nop 0
	v_mul_f32_e32 v89, 0x45800000, v88
	v_cndmask_b32_e32 v88, v88, v89, vcc
	s_waitcnt lgkmcnt(0)
	v_pk_mul_f32 v[80:81], v[80:81], v[88:89] op_sel_hi:[1,0]
	v_pk_mul_f32 v[82:83], v[82:83], v[88:89] op_sel_hi:[1,0]
	v_pk_mul_f32 v[84:85], v[84:85], v[88:89] op_sel_hi:[1,0]
	v_pk_mul_f32 v[86:87], v[86:87], v[88:89] op_sel_hi:[1,0]
	v_pk_fma_f32 v[80:81], v[220:221], v[80:81], v[166:167]
	v_pk_fma_f32 v[82:83], v[222:223], v[82:83], v[168:169]
	v_pk_fma_f32 v[84:85], v[224:225], v[84:85], v[170:171]
	v_pk_fma_f32 v[86:87], v[226:227], v[86:87], v[172:173]
	global_store_dwordx4 v[90:91], v[80:83], off
	global_store_dwordx4 v[90:91], v[84:87], off offset:16
	ds_read_b128 v[96:99], v136 offset:12480
	ds_read_b128 v[100:103], v136 offset:12496
	v_add_u32_e32 v106, 12, v130
	v_ashrrev_i32_e32 v107, 31, v106
	v_lshlrev_b64 v[106:107], 12, v[106:107]
	v_lshl_add_u64 v[106:107], v[68:69], 0, v[106:107]
	s_waitcnt vmcnt(10)
	v_fmamk_f32 v104, v231, 0x3a800000, v70
	v_mul_f32_e32 v105, 0x4b800000, v104
	v_cmp_gt_f32_e32 vcc, s7, v104
	s_nop 1
	v_cndmask_b32_e32 v104, v104, v105, vcc
	v_rsq_f32_e32 v104, v104
	s_nop 0
	v_mul_f32_e32 v105, 0x45800000, v104
	v_cndmask_b32_e32 v104, v104, v105, vcc
	s_waitcnt lgkmcnt(0)
	v_pk_mul_f32 v[96:97], v[96:97], v[104:105] op_sel_hi:[1,0]
	v_pk_mul_f32 v[98:99], v[98:99], v[104:105] op_sel_hi:[1,0]
	v_pk_mul_f32 v[100:101], v[100:101], v[104:105] op_sel_hi:[1,0]
	v_pk_mul_f32 v[102:103], v[102:103], v[104:105] op_sel_hi:[1,0]
	v_pk_fma_f32 v[96:97], v[220:221], v[96:97], v[174:175]
	v_pk_fma_f32 v[98:99], v[222:223], v[98:99], v[176:177]
	v_pk_fma_f32 v[100:101], v[224:225], v[100:101], v[178:179]
	v_pk_fma_f32 v[102:103], v[226:227], v[102:103], v[180:181]
	global_store_dwordx4 v[106:107], v[96:99], off
	global_store_dwordx4 v[106:107], v[100:103], off offset:16
	ds_read_b128 v[80:83], v136 offset:16640
	ds_read_b128 v[84:87], v136 offset:16656
	v_add_u32_e32 v90, 16, v130
	v_ashrrev_i32_e32 v91, 31, v90
	v_lshlrev_b64 v[90:91], 12, v[90:91]
	v_lshl_add_u64 v[90:91], v[68:69], 0, v[90:91]
	s_waitcnt vmcnt(11)
	v_fmamk_f32 v88, v232, 0x3a800000, v70
	v_mul_f32_e32 v89, 0x4b800000, v88
	v_cmp_gt_f32_e32 vcc, s7, v88
	s_nop 1
	v_cndmask_b32_e32 v88, v88, v89, vcc
	v_rsq_f32_e32 v88, v88
	s_nop 0
	v_mul_f32_e32 v89, 0x45800000, v88
	v_cndmask_b32_e32 v88, v88, v89, vcc
	s_waitcnt lgkmcnt(0)
	v_pk_mul_f32 v[80:81], v[80:81], v[88:89] op_sel_hi:[1,0]
	v_pk_mul_f32 v[82:83], v[82:83], v[88:89] op_sel_hi:[1,0]
	v_pk_mul_f32 v[84:85], v[84:85], v[88:89] op_sel_hi:[1,0]
	v_pk_mul_f32 v[86:87], v[86:87], v[88:89] op_sel_hi:[1,0]
	v_pk_fma_f32 v[80:81], v[220:221], v[80:81], v[182:183]
	v_pk_fma_f32 v[82:83], v[222:223], v[82:83], v[184:185]
	v_pk_fma_f32 v[84:85], v[224:225], v[84:85], v[186:187]
	v_pk_fma_f32 v[86:87], v[226:227], v[86:87], v[188:189]
	global_store_dwordx4 v[90:91], v[80:83], off
	global_store_dwordx4 v[90:91], v[84:87], off offset:16
	ds_read_b128 v[96:99], v136 offset:20800
	ds_read_b128 v[100:103], v136 offset:20816
	v_add_u32_e32 v106, 20, v130
	v_ashrrev_i32_e32 v107, 31, v106
	v_lshlrev_b64 v[106:107], 12, v[106:107]
	v_lshl_add_u64 v[106:107], v[68:69], 0, v[106:107]
	s_waitcnt vmcnt(12)
	v_fmamk_f32 v104, v233, 0x3a800000, v70
	v_mul_f32_e32 v105, 0x4b800000, v104
	v_cmp_gt_f32_e32 vcc, s7, v104
	s_nop 1
	v_cndmask_b32_e32 v104, v104, v105, vcc
	v_rsq_f32_e32 v104, v104
	s_nop 0
	v_mul_f32_e32 v105, 0x45800000, v104
	v_cndmask_b32_e32 v104, v104, v105, vcc
	s_waitcnt lgkmcnt(0)
	v_pk_mul_f32 v[96:97], v[96:97], v[104:105] op_sel_hi:[1,0]
	v_pk_mul_f32 v[98:99], v[98:99], v[104:105] op_sel_hi:[1,0]
	v_pk_mul_f32 v[100:101], v[100:101], v[104:105] op_sel_hi:[1,0]
	v_pk_mul_f32 v[102:103], v[102:103], v[104:105] op_sel_hi:[1,0]
	v_pk_fma_f32 v[96:97], v[220:221], v[96:97], v[190:191]
	v_pk_fma_f32 v[98:99], v[222:223], v[98:99], v[192:193]
	v_pk_fma_f32 v[100:101], v[224:225], v[100:101], v[194:195]
	v_pk_fma_f32 v[102:103], v[226:227], v[102:103], v[196:197]
	global_store_dwordx4 v[106:107], v[96:99], off
	global_store_dwordx4 v[106:107], v[100:103], off offset:16
	ds_read_b128 v[80:83], v136 offset:24960
	ds_read_b128 v[84:87], v136 offset:24976
	v_add_u32_e32 v90, 24, v130
	v_ashrrev_i32_e32 v91, 31, v90
	v_lshlrev_b64 v[90:91], 12, v[90:91]
	v_lshl_add_u64 v[90:91], v[68:69], 0, v[90:91]
	s_waitcnt vmcnt(13)
	v_fmamk_f32 v88, v234, 0x3a800000, v70
	v_mul_f32_e32 v89, 0x4b800000, v88
	v_cmp_gt_f32_e32 vcc, s7, v88
	s_nop 1
	v_cndmask_b32_e32 v88, v88, v89, vcc
	v_rsq_f32_e32 v88, v88
	s_nop 0
	v_mul_f32_e32 v89, 0x45800000, v88
	v_cndmask_b32_e32 v88, v88, v89, vcc
	s_waitcnt lgkmcnt(0)
	v_pk_mul_f32 v[80:81], v[80:81], v[88:89] op_sel_hi:[1,0]
	v_pk_mul_f32 v[82:83], v[82:83], v[88:89] op_sel_hi:[1,0]
	v_pk_mul_f32 v[84:85], v[84:85], v[88:89] op_sel_hi:[1,0]
	v_pk_mul_f32 v[86:87], v[86:87], v[88:89] op_sel_hi:[1,0]
	v_pk_fma_f32 v[80:81], v[220:221], v[80:81], v[198:199]
	v_pk_fma_f32 v[82:83], v[222:223], v[82:83], v[200:201]
	v_pk_fma_f32 v[84:85], v[224:225], v[84:85], v[202:203]
	v_pk_fma_f32 v[86:87], v[226:227], v[86:87], v[204:205]
	global_store_dwordx4 v[90:91], v[80:83], off
	global_store_dwordx4 v[90:91], v[84:87], off offset:16
	ds_read_b128 v[96:99], v136 offset:29120
	ds_read_b128 v[100:103], v136 offset:29136
	v_add_u32_e32 v106, 28, v130
	v_ashrrev_i32_e32 v107, 31, v106
	v_lshlrev_b64 v[106:107], 12, v[106:107]
	v_lshl_add_u64 v[106:107], v[68:69], 0, v[106:107]
	s_waitcnt vmcnt(14)
	v_fmamk_f32 v104, v235, 0x3a800000, v70
	v_mul_f32_e32 v105, 0x4b800000, v104
	v_cmp_gt_f32_e32 vcc, s7, v104
	s_nop 1
	v_cndmask_b32_e32 v104, v104, v105, vcc
	v_rsq_f32_e32 v104, v104
	s_nop 0
	v_mul_f32_e32 v105, 0x45800000, v104
	v_cndmask_b32_e32 v104, v104, v105, vcc
	s_waitcnt lgkmcnt(0)
	v_pk_mul_f32 v[96:97], v[96:97], v[104:105] op_sel_hi:[1,0]
	v_pk_mul_f32 v[98:99], v[98:99], v[104:105] op_sel_hi:[1,0]
	v_pk_mul_f32 v[100:101], v[100:101], v[104:105] op_sel_hi:[1,0]
	v_pk_mul_f32 v[102:103], v[102:103], v[104:105] op_sel_hi:[1,0]
	v_pk_fma_f32 v[96:97], v[220:221], v[96:97], v[206:207]
	v_pk_fma_f32 v[98:99], v[222:223], v[98:99], v[208:209]
	v_pk_fma_f32 v[100:101], v[224:225], v[100:101], v[210:211]
	v_pk_fma_f32 v[102:103], v[226:227], v[102:103], v[212:213]
	global_store_dwordx4 v[106:107], v[96:99], off
	global_store_dwordx4 v[106:107], v[100:103], off offset:16
	s_waitcnt lgkmcnt(0)
	s_barrier
	ds_write2_b32 v219, v56, v60 offset1:16
	v_add_u32_e32 v56, 0x400, v219
	ds_write2_b32 v56, v57, v61 offset0:4 offset1:20
	v_add_u32_e32 v57, 0x800, v219
	ds_write2_b32 v57, v58, v62 offset0:8 offset1:24
	v_add_u32_e32 v58, 0xc00, v219
	ds_write2_b32 v58, v59, v63 offset0:12 offset1:28
	v_add_u32_e32 v59, 0x4000, v219
	ds_write2_b32 v59, v48, v52 offset0:64 offset1:80
	v_add_u32_e32 v48, 0x4400, v219
	ds_write2_b32 v48, v49, v53 offset0:68 offset1:84
	v_add_u32_e32 v49, 0x4800, v219
	ds_write2_b32 v49, v50, v54 offset0:72 offset1:88
	v_add_u32_e32 v50, 0x4c00, v219
	ds_write2_b32 v50, v51, v55 offset0:76 offset1:92
	v_add_u32_e32 v51, 0x8000, v219
	ds_write2_b32 v51, v32, v44 offset0:128 offset1:144
	v_add_u32_e32 v32, 0x8400, v219
	ds_write2_b32 v32, v33, v45 offset0:132 offset1:148
	v_add_u32_e32 v33, 0x8800, v219
	ds_write2_b32 v33, v34, v46 offset0:136 offset1:152
	v_add_u32_e32 v34, 0x8c00, v219
	ds_write2_b32 v34, v35, v47 offset0:140 offset1:156
	v_add_u32_e32 v35, 0xc000, v219
	ds_write2_b32 v35, v0, v12 offset0:192 offset1:208
	v_add_u32_e32 v0, 0xc400, v219
	ds_write2_b32 v0, v1, v13 offset0:196 offset1:212
	v_add_u32_e32 v1, 0xc800, v219
	ds_write2_b32 v1, v2, v14 offset0:200 offset1:216
	v_add_u32_e32 v2, 0xcc00, v219
	ds_write2_b32 v2, v3, v15 offset0:204 offset1:220
	ds_write2_b32 v219, v16, v36 offset0:128 offset1:144
	ds_write2_b32 v56, v17, v37 offset0:132 offset1:148
	ds_write2_b32 v57, v18, v38 offset0:136 offset1:152
	ds_write2_b32 v58, v19, v39 offset0:140 offset1:156
	ds_write2_b32 v59, v20, v40 offset0:192 offset1:208
	ds_write2_b32 v48, v21, v41 offset0:196 offset1:212
	ds_write2_b32 v49, v22, v42 offset0:200 offset1:216
	ds_write2_b32 v50, v23, v43 offset0:204 offset1:220
	ds_write2_b32 v32, v8, v28 offset1:16
	ds_write2_b32 v33, v9, v29 offset0:4 offset1:20
	ds_write2_b32 v34, v10, v30 offset0:8 offset1:24
	v_add_u32_e32 v3, 0x9000, v219
	ds_write2_b32 v3, v11, v31 offset0:12 offset1:28
	ds_write2_b32 v0, v4, v24 offset0:64 offset1:80
	ds_write2_b32 v1, v5, v25 offset0:68 offset1:84
	ds_write2_b32 v2, v6, v26 offset0:72 offset1:88
	v_add_u32_e32 v0, 0xd000, v219
	ds_write2_b32 v0, v7, v27 offset0:76 offset1:92
	s_mov_b32 s6, 0
	v_mov_b32_e32 v0, 0x358637bd
	s_mov_b32 s7, 0x800000
	s_waitcnt lgkmcnt(0)
	s_barrier
	global_load_dwordx4 v[72:75], v[64:65], off
	global_load_dwordx4 v[76:79], v[64:65], off offset:16
	v_add_u32_e32 v94, -4, v128
	v_ashrrev_i32_e32 v95, 31, v94
	v_lshl_add_u64 v[92:93], v[94:95], 2, s[2:3]
	v_lshlrev_b64 v[94:95], 12, v[94:95]
	global_load_dword v204, v[92:93], off sc1
	v_lshl_add_u64 v[94:95], v[66:67], 0, v[94:95]
	global_load_dwordx4 v[140:143], v[94:95], off
	global_load_dwordx4 v[144:147], v[94:95], off offset:16
	v_add_u32_e32 v94, 0, v128
	v_ashrrev_i32_e32 v95, 31, v94
	v_lshl_add_u64 v[92:93], v[94:95], 2, s[2:3]
	v_lshlrev_b64 v[94:95], 12, v[94:95]
	global_load_dword v205, v[92:93], off sc1
	v_lshl_add_u64 v[94:95], v[66:67], 0, v[94:95]
	global_load_dwordx4 v[148:151], v[94:95], off
	global_load_dwordx4 v[152:155], v[94:95], off offset:16
	v_add_u32_e32 v94, 4, v128
	v_ashrrev_i32_e32 v95, 31, v94
	v_lshl_add_u64 v[92:93], v[94:95], 2, s[2:3]
	v_lshlrev_b64 v[94:95], 12, v[94:95]
	global_load_dword v206, v[92:93], off sc1
	v_lshl_add_u64 v[94:95], v[66:67], 0, v[94:95]
	global_load_dwordx4 v[156:159], v[94:95], off
	global_load_dwordx4 v[160:163], v[94:95], off offset:16
	v_add_u32_e32 v94, 8, v128
	v_ashrrev_i32_e32 v95, 31, v94
	v_lshl_add_u64 v[92:93], v[94:95], 2, s[2:3]
	v_lshlrev_b64 v[94:95], 12, v[94:95]
	global_load_dword v207, v[92:93], off sc1
	v_lshl_add_u64 v[94:95], v[66:67], 0, v[94:95]
	global_load_dwordx4 v[164:167], v[94:95], off
	global_load_dwordx4 v[168:171], v[94:95], off offset:16
	v_add_u32_e32 v94, 12, v128
	v_ashrrev_i32_e32 v95, 31, v94
	v_lshl_add_u64 v[92:93], v[94:95], 2, s[2:3]
	v_lshlrev_b64 v[94:95], 12, v[94:95]
	global_load_dword v208, v[92:93], off sc1
	v_lshl_add_u64 v[94:95], v[66:67], 0, v[94:95]
	global_load_dwordx4 v[172:175], v[94:95], off
	global_load_dwordx4 v[176:179], v[94:95], off offset:16
	v_add_u32_e32 v94, 16, v128
	v_ashrrev_i32_e32 v95, 31, v94
	v_lshl_add_u64 v[92:93], v[94:95], 2, s[2:3]
	v_lshlrev_b64 v[94:95], 12, v[94:95]
	global_load_dword v209, v[92:93], off sc1
	v_lshl_add_u64 v[94:95], v[66:67], 0, v[94:95]
	global_load_dwordx4 v[180:183], v[94:95], off
	global_load_dwordx4 v[184:187], v[94:95], off offset:16
	v_add_u32_e32 v94, 20, v128
	v_ashrrev_i32_e32 v95, 31, v94
	v_lshl_add_u64 v[92:93], v[94:95], 2, s[2:3]
	v_lshlrev_b64 v[94:95], 12, v[94:95]
	global_load_dword v210, v[92:93], off sc1
	v_lshl_add_u64 v[94:95], v[66:67], 0, v[94:95]
	global_load_dwordx4 v[188:191], v[94:95], off
	global_load_dwordx4 v[192:195], v[94:95], off offset:16
	v_add_u32_e32 v94, 24, v128
	v_ashrrev_i32_e32 v95, 31, v94
	v_lshl_add_u64 v[92:93], v[94:95], 2, s[2:3]
	v_lshlrev_b64 v[94:95], 12, v[94:95]
	global_load_dword v211, v[92:93], off sc1
	v_lshl_add_u64 v[94:95], v[66:67], 0, v[94:95]
	global_load_dwordx4 v[196:199], v[94:95], off
	global_load_dwordx4 v[200:203], v[94:95], off offset:16
	ds_read_b128 v[80:83], v136 offset:0
	ds_read_b128 v[84:87], v136 offset:16
	v_add_u32_e32 v90, -4, v128
	v_ashrrev_i32_e32 v91, 31, v90
	v_lshlrev_b64 v[90:91], 12, v[90:91]
	v_lshl_add_u64 v[90:91], v[68:69], 0, v[90:91]
	s_waitcnt vmcnt(21)
	v_fmamk_f32 v88, v204, 0x3a800000, v0
	v_mul_f32_e32 v89, 0x4b800000, v88
	v_cmp_gt_f32_e32 vcc, s7, v88
	s_nop 1
	v_cndmask_b32_e32 v88, v88, v89, vcc
	v_rsq_f32_e32 v88, v88
	s_nop 0
	v_mul_f32_e32 v89, 0x45800000, v88
	v_cndmask_b32_e32 v88, v88, v89, vcc
	s_waitcnt lgkmcnt(0)
	v_pk_mul_f32 v[80:81], v[80:81], v[88:89] op_sel_hi:[1,0]
	v_pk_mul_f32 v[82:83], v[82:83], v[88:89] op_sel_hi:[1,0]
	v_pk_mul_f32 v[84:85], v[84:85], v[88:89] op_sel_hi:[1,0]
	v_pk_mul_f32 v[86:87], v[86:87], v[88:89] op_sel_hi:[1,0]
	v_pk_fma_f32 v[80:81], v[72:73], v[80:81], v[140:141]
	v_pk_fma_f32 v[82:83], v[74:75], v[82:83], v[142:143]
	v_pk_fma_f32 v[84:85], v[76:77], v[84:85], v[144:145]
	v_pk_fma_f32 v[86:87], v[78:79], v[86:87], v[146:147]
	global_store_dwordx4 v[90:91], v[80:83], off
	global_store_dwordx4 v[90:91], v[84:87], off offset:16
	ds_read_b128 v[96:99], v136 offset:4160
	ds_read_b128 v[100:103], v136 offset:4176
	v_add_u32_e32 v106, 0, v128
	v_ashrrev_i32_e32 v107, 31, v106
	v_lshlrev_b64 v[106:107], 12, v[106:107]
	v_lshl_add_u64 v[106:107], v[68:69], 0, v[106:107]
	s_waitcnt vmcnt(20)
	v_fmamk_f32 v104, v205, 0x3a800000, v0
	v_mul_f32_e32 v105, 0x4b800000, v104
	v_cmp_gt_f32_e32 vcc, s7, v104
	s_nop 1
	v_cndmask_b32_e32 v104, v104, v105, vcc
	v_rsq_f32_e32 v104, v104
	s_nop 0
	v_mul_f32_e32 v105, 0x45800000, v104
	v_cndmask_b32_e32 v104, v104, v105, vcc
	s_waitcnt lgkmcnt(0)
	v_pk_mul_f32 v[96:97], v[96:97], v[104:105] op_sel_hi:[1,0]
	v_pk_mul_f32 v[98:99], v[98:99], v[104:105] op_sel_hi:[1,0]
	v_pk_mul_f32 v[100:101], v[100:101], v[104:105] op_sel_hi:[1,0]
	v_pk_mul_f32 v[102:103], v[102:103], v[104:105] op_sel_hi:[1,0]
	v_pk_fma_f32 v[96:97], v[72:73], v[96:97], v[148:149]
	v_pk_fma_f32 v[98:99], v[74:75], v[98:99], v[150:151]
	v_pk_fma_f32 v[100:101], v[76:77], v[100:101], v[152:153]
	v_pk_fma_f32 v[102:103], v[78:79], v[102:103], v[154:155]
	global_store_dwordx4 v[106:107], v[96:99], off
	global_store_dwordx4 v[106:107], v[100:103], off offset:16
	ds_read_b128 v[80:83], v136 offset:8320
	ds_read_b128 v[84:87], v136 offset:8336
	v_add_u32_e32 v90, 4, v128
	v_ashrrev_i32_e32 v91, 31, v90
	v_lshlrev_b64 v[90:91], 12, v[90:91]
	v_lshl_add_u64 v[90:91], v[68:69], 0, v[90:91]
	s_waitcnt vmcnt(19)
	v_fmamk_f32 v88, v206, 0x3a800000, v0
	v_mul_f32_e32 v89, 0x4b800000, v88
	v_cmp_gt_f32_e32 vcc, s7, v88
	s_nop 1
	v_cndmask_b32_e32 v88, v88, v89, vcc
	v_rsq_f32_e32 v88, v88
	s_nop 0
	v_mul_f32_e32 v89, 0x45800000, v88
	v_cndmask_b32_e32 v88, v88, v89, vcc
	s_waitcnt lgkmcnt(0)
	v_pk_mul_f32 v[80:81], v[80:81], v[88:89] op_sel_hi:[1,0]
	v_pk_mul_f32 v[82:83], v[82:83], v[88:89] op_sel_hi:[1,0]
	v_pk_mul_f32 v[84:85], v[84:85], v[88:89] op_sel_hi:[1,0]
	v_pk_mul_f32 v[86:87], v[86:87], v[88:89] op_sel_hi:[1,0]
	v_pk_fma_f32 v[80:81], v[72:73], v[80:81], v[156:157]
	v_pk_fma_f32 v[82:83], v[74:75], v[82:83], v[158:159]
	v_pk_fma_f32 v[84:85], v[76:77], v[84:85], v[160:161]
	v_pk_fma_f32 v[86:87], v[78:79], v[86:87], v[162:163]
	global_store_dwordx4 v[90:91], v[80:83], off
	global_store_dwordx4 v[90:91], v[84:87], off offset:16
	ds_read_b128 v[96:99], v136 offset:12480
	ds_read_b128 v[100:103], v136 offset:12496
	v_add_u32_e32 v106, 8, v128
	v_ashrrev_i32_e32 v107, 31, v106
	v_lshlrev_b64 v[106:107], 12, v[106:107]
	v_lshl_add_u64 v[106:107], v[68:69], 0, v[106:107]
	s_waitcnt vmcnt(18)
	v_fmamk_f32 v104, v207, 0x3a800000, v0
	v_mul_f32_e32 v105, 0x4b800000, v104
	v_cmp_gt_f32_e32 vcc, s7, v104
	s_nop 1
	v_cndmask_b32_e32 v104, v104, v105, vcc
	v_rsq_f32_e32 v104, v104
	s_nop 0
	v_mul_f32_e32 v105, 0x45800000, v104
	v_cndmask_b32_e32 v104, v104, v105, vcc
	s_waitcnt lgkmcnt(0)
	v_pk_mul_f32 v[96:97], v[96:97], v[104:105] op_sel_hi:[1,0]
	v_pk_mul_f32 v[98:99], v[98:99], v[104:105] op_sel_hi:[1,0]
	v_pk_mul_f32 v[100:101], v[100:101], v[104:105] op_sel_hi:[1,0]
	v_pk_mul_f32 v[102:103], v[102:103], v[104:105] op_sel_hi:[1,0]
	v_pk_fma_f32 v[96:97], v[72:73], v[96:97], v[164:165]
	v_pk_fma_f32 v[98:99], v[74:75], v[98:99], v[166:167]
	v_pk_fma_f32 v[100:101], v[76:77], v[100:101], v[168:169]
	v_pk_fma_f32 v[102:103], v[78:79], v[102:103], v[170:171]
	global_store_dwordx4 v[106:107], v[96:99], off
	global_store_dwordx4 v[106:107], v[100:103], off offset:16
	ds_read_b128 v[80:83], v136 offset:16640
	ds_read_b128 v[84:87], v136 offset:16656
	v_add_u32_e32 v90, 12, v128
	v_ashrrev_i32_e32 v91, 31, v90
	v_lshlrev_b64 v[90:91], 12, v[90:91]
	v_lshl_add_u64 v[90:91], v[68:69], 0, v[90:91]
	s_waitcnt vmcnt(17)
	v_fmamk_f32 v88, v208, 0x3a800000, v0
	v_mul_f32_e32 v89, 0x4b800000, v88
	v_cmp_gt_f32_e32 vcc, s7, v88
	s_nop 1
	v_cndmask_b32_e32 v88, v88, v89, vcc
	v_rsq_f32_e32 v88, v88
	s_nop 0
	v_mul_f32_e32 v89, 0x45800000, v88
	v_cndmask_b32_e32 v88, v88, v89, vcc
	s_waitcnt lgkmcnt(0)
	v_pk_mul_f32 v[80:81], v[80:81], v[88:89] op_sel_hi:[1,0]
	v_pk_mul_f32 v[82:83], v[82:83], v[88:89] op_sel_hi:[1,0]
	v_pk_mul_f32 v[84:85], v[84:85], v[88:89] op_sel_hi:[1,0]
	v_pk_mul_f32 v[86:87], v[86:87], v[88:89] op_sel_hi:[1,0]
	v_pk_fma_f32 v[80:81], v[72:73], v[80:81], v[172:173]
	v_pk_fma_f32 v[82:83], v[74:75], v[82:83], v[174:175]
	v_pk_fma_f32 v[84:85], v[76:77], v[84:85], v[176:177]
	v_pk_fma_f32 v[86:87], v[78:79], v[86:87], v[178:179]
	global_store_dwordx4 v[90:91], v[80:83], off
	global_store_dwordx4 v[90:91], v[84:87], off offset:16
	ds_read_b128 v[96:99], v136 offset:20800
	ds_read_b128 v[100:103], v136 offset:20816
	v_add_u32_e32 v106, 16, v128
	v_ashrrev_i32_e32 v107, 31, v106
	v_lshlrev_b64 v[106:107], 12, v[106:107]
	v_lshl_add_u64 v[106:107], v[68:69], 0, v[106:107]
	s_waitcnt vmcnt(16)
	v_fmamk_f32 v104, v209, 0x3a800000, v0
	v_mul_f32_e32 v105, 0x4b800000, v104
	v_cmp_gt_f32_e32 vcc, s7, v104
	s_nop 1
	v_cndmask_b32_e32 v104, v104, v105, vcc
	v_rsq_f32_e32 v104, v104
	s_nop 0
	v_mul_f32_e32 v105, 0x45800000, v104
	v_cndmask_b32_e32 v104, v104, v105, vcc
	s_waitcnt lgkmcnt(0)
	v_pk_mul_f32 v[96:97], v[96:97], v[104:105] op_sel_hi:[1,0]
	v_pk_mul_f32 v[98:99], v[98:99], v[104:105] op_sel_hi:[1,0]
	v_pk_mul_f32 v[100:101], v[100:101], v[104:105] op_sel_hi:[1,0]
	v_pk_mul_f32 v[102:103], v[102:103], v[104:105] op_sel_hi:[1,0]
	v_pk_fma_f32 v[96:97], v[72:73], v[96:97], v[180:181]
	v_pk_fma_f32 v[98:99], v[74:75], v[98:99], v[182:183]
	v_pk_fma_f32 v[100:101], v[76:77], v[100:101], v[184:185]
	v_pk_fma_f32 v[102:103], v[78:79], v[102:103], v[186:187]
	global_store_dwordx4 v[106:107], v[96:99], off
	global_store_dwordx4 v[106:107], v[100:103], off offset:16
	ds_read_b128 v[80:83], v136 offset:24960
	ds_read_b128 v[84:87], v136 offset:24976
	v_add_u32_e32 v90, 20, v128
	v_ashrrev_i32_e32 v91, 31, v90
	v_lshlrev_b64 v[90:91], 12, v[90:91]
	v_lshl_add_u64 v[90:91], v[68:69], 0, v[90:91]
	s_waitcnt vmcnt(15)
	v_fmamk_f32 v88, v210, 0x3a800000, v0
	v_mul_f32_e32 v89, 0x4b800000, v88
	v_cmp_gt_f32_e32 vcc, s7, v88
	s_nop 1
	v_cndmask_b32_e32 v88, v88, v89, vcc
	v_rsq_f32_e32 v88, v88
	s_nop 0
	v_mul_f32_e32 v89, 0x45800000, v88
	v_cndmask_b32_e32 v88, v88, v89, vcc
	s_waitcnt lgkmcnt(0)
	v_pk_mul_f32 v[80:81], v[80:81], v[88:89] op_sel_hi:[1,0]
	v_pk_mul_f32 v[82:83], v[82:83], v[88:89] op_sel_hi:[1,0]
	v_pk_mul_f32 v[84:85], v[84:85], v[88:89] op_sel_hi:[1,0]
	v_pk_mul_f32 v[86:87], v[86:87], v[88:89] op_sel_hi:[1,0]
	v_pk_fma_f32 v[80:81], v[72:73], v[80:81], v[188:189]
	v_pk_fma_f32 v[82:83], v[74:75], v[82:83], v[190:191]
	v_pk_fma_f32 v[84:85], v[76:77], v[84:85], v[192:193]
	v_pk_fma_f32 v[86:87], v[78:79], v[86:87], v[194:195]
	global_store_dwordx4 v[90:91], v[80:83], off
	global_store_dwordx4 v[90:91], v[84:87], off offset:16
	ds_read_b128 v[96:99], v136 offset:29120
	ds_read_b128 v[100:103], v136 offset:29136
	v_add_u32_e32 v106, 24, v128
	v_ashrrev_i32_e32 v107, 31, v106
	v_lshlrev_b64 v[106:107], 12, v[106:107]
	v_lshl_add_u64 v[106:107], v[68:69], 0, v[106:107]
	s_waitcnt vmcnt(14)
	v_fmamk_f32 v104, v211, 0x3a800000, v0
	v_mul_f32_e32 v105, 0x4b800000, v104
	v_cmp_gt_f32_e32 vcc, s7, v104
	s_nop 1
	v_cndmask_b32_e32 v104, v104, v105, vcc
	v_rsq_f32_e32 v104, v104
	s_nop 0
	v_mul_f32_e32 v105, 0x45800000, v104
	v_cndmask_b32_e32 v104, v104, v105, vcc
	s_waitcnt lgkmcnt(0)
	v_pk_mul_f32 v[96:97], v[96:97], v[104:105] op_sel_hi:[1,0]
	v_pk_mul_f32 v[98:99], v[98:99], v[104:105] op_sel_hi:[1,0]
	v_pk_mul_f32 v[100:101], v[100:101], v[104:105] op_sel_hi:[1,0]
	v_pk_mul_f32 v[102:103], v[102:103], v[104:105] op_sel_hi:[1,0]
	v_pk_fma_f32 v[96:97], v[72:73], v[96:97], v[196:197]
	v_pk_fma_f32 v[98:99], v[74:75], v[98:99], v[198:199]
	v_pk_fma_f32 v[100:101], v[76:77], v[100:101], v[200:201]
	v_pk_fma_f32 v[102:103], v[78:79], v[102:103], v[202:203]
	global_store_dwordx4 v[106:107], v[96:99], off
	global_store_dwordx4 v[106:107], v[100:103], off offset:16
	s_branch .LBB0_616
